# v73 plus attention tile loop: K/V ring wrap folded into the scalar stage offset (12 v_subrev per tile removed)
# speedup vs baseline: 1.0023x; 1.0023x over previous
.LBB0_260:
	v_sub_f32_e32 v51, v96, v48
	v_exp_f32_e32 v51, v51
	v_sub_f32_e32 v55, v69, v48
	v_exp_f32_e32 v55, v55
	v_sub_f32_e32 v57, v65, v48
	v_exp_f32_e32 v57, v57
	v_sub_f32_e32 v50, v50, v48
	v_exp_f32_e32 v50, v50
	v_sub_f32_e32 v15, v15, v48
	v_add_f32_e32 v52, 0, v51
	v_exp_f32_e32 v15, v15
	v_sub_f32_e32 v14, v14, v48
	v_add_f32_e32 v52, v55, v52
	v_exp_f32_e32 v14, v14
	v_sub_f32_e32 v13, v13, v48
	v_add_f32_e32 v52, v57, v52
	v_exp_f32_e32 v13, v13
	v_sub_f32_e32 v12, v12, v48
	v_add_f32_e32 v52, v50, v52
	v_exp_f32_e32 v12, v12
	v_sub_f32_e32 v11, v11, v48
	v_add_f32_e32 v52, v15, v52
	v_exp_f32_e32 v59, v11
	v_sub_f32_e32 v10, v10, v48
	v_add_f32_e32 v52, v14, v52
	v_exp_f32_e32 v60, v10
	v_sub_f32_e32 v9, v9, v48
	v_add_f32_e32 v52, v13, v52
	v_exp_f32_e32 v61, v9
	v_sub_f32_e32 v8, v8, v48
	v_sub_f32_e32 v53, v70, v48
	v_add_f32_e32 v52, v12, v52
	v_exp_f32_e32 v62, v8
	v_sub_f32_e32 v7, v7, v48
	v_exp_f32_e32 v54, v53
	v_sub_f32_e32 v56, v68, v48
	v_add_f32_e32 v11, v59, v52
	v_exp_f32_e32 v63, v7
	v_sub_f32_e32 v6, v6, v48
	v_exp_f32_e32 v56, v56
	v_sub_f32_e32 v58, v64, v48
	v_add_f32_e32 v10, v60, v11
	v_exp_f32_e32 v64, v6
	v_sub_f32_e32 v5, v5, v48
	v_exp_f32_e32 v58, v58
	v_sub_f32_e32 v49, v49, v48
	v_add_f32_e32 v9, v61, v10
	v_exp_f32_e32 v65, v5
	v_sub_f32_e32 v4, v4, v48
	v_exp_f32_e32 v49, v49
	v_add_f32_e32 v8, v62, v9
	v_exp_f32_e32 v66, v4
	v_add_f32_e32 v53, 0, v54
	v_add_f32_e32 v7, v63, v8
	v_add_f32_e32 v53, v56, v53
	v_add_f32_e32 v6, v64, v7
	v_add_f32_e32 v53, v58, v53
	v_add_f32_e32 v5, v65, v6
	v_add_f32_e32 v53, v49, v53
	v_add_f32_e32 v4, v66, v5
	v_add_f32_e32 v67, v53, v4
	v_fmac_f32_e32 v67, v177, v0
	v_add_u32_e32 v0, v185, v172
	ds_read2st64_b64 v[8:11], v0 offset1:8
	v_add_u32_e32 v0, v185, v170
	v_cvt_pkrtz_f16_f32 v6, v15, v14
	v_cvt_pkrtz_f16_f32 v7, v13, v12
	ds_read2st64_b64 v[12:15], v0 offset1:8
	v_cvt_pkrtz_f16_f32 v4, v51, v55
	v_cvt_pkrtz_f16_f32 v5, v57, v50
	s_waitcnt lgkmcnt(0)
	v_mov_b32_e32 v50, v8
	v_mov_b32_e32 v51, v9
	v_mov_b32_e32 v52, v12
	v_mov_b32_e32 v53, v13
	v_mov_b32_e32 v12, v10
	v_mov_b32_e32 v13, v11
	v_add_u32_e32 v0, v185, v169
	ds_read2st64_b64 v[8:11], v0 offset1:8
	v_add_u32_e32 v0, v185, v168
	v_mfma_f32_32x32x16_f16 v[32:47], v[12:15], v[4:7], v[32:47]
	ds_read2st64_b64 v[12:15], v0 offset1:8
	v_cvt_pkrtz_f16_f32 v0, v54, v56
	v_cvt_pkrtz_f16_f32 v1, v58, v49
	v_mov_b32_e32 v2, v3
	v_mov_b32_e32 v177, v67
	v_mfma_f32_32x32x16_f16 v[16:31], v[50:53], v[4:7], v[16:31]
	s_waitcnt lgkmcnt(0)
	v_mov_b32_e32 v50, v8
	v_mov_b32_e32 v51, v9
	v_mov_b32_e32 v52, v12
	v_mov_b32_e32 v53, v13
	v_mov_b32_e32 v12, v10
	v_mov_b32_e32 v13, v11
	v_cvt_pkrtz_f16_f32 v4, v59, v60
	v_cvt_pkrtz_f16_f32 v5, v61, v62
	v_cvt_pkrtz_f16_f32 v6, v63, v64
	v_cvt_pkrtz_f16_f32 v7, v65, v66
	v_add_u32_e32 v8, v185, v164
	ds_read2st64_b64 v[8:11], v8 offset0:16 offset1:24
	v_mfma_f32_32x32x16_f16 v[16:31], v[50:53], v[4:7], v[16:31]
	v_mfma_f32_32x32x16_f16 v[32:47], v[12:15], v[4:7], v[32:47]
	v_add_u32_e32 v4, v185, v166
	ds_read2st64_b64 v[4:7], v4 offset1:8
	s_waitcnt lgkmcnt(0)
	v_mov_b32_e32 v14, v8
	v_mov_b32_e32 v15, v9
	v_mov_b32_e32 v12, v4
	v_mov_b32_e32 v13, v5
	v_mov_b32_e32 v8, v6
	v_mov_b32_e32 v9, v7
	v_mfma_f32_32x32x16_f16 v[16:31], v[12:15], v[0:3], v[16:31]
	s_nop 0
	v_mfma_f32_32x32x16_f16 v[32:47], v[8:11], v[0:3], v[32:47]

.LBB0_291:
	s_or_b64 exec, exec, s[36:37]
	s_mul_hi_u32 s36, s54, 0xaaaaaaab
	s_lshr_b32 s36, s36, 2
	s_mul_i32 s36, s36, 0x18000
	s_sub_i32 s32, s53, s36
	s_barrier
	v_cmp_ge_i32_e32 vcc, s54, v123
	s_or_b64 s[36:37], s[48:49], vcc
	s_and_saveexec_b64 s[44:45], s[36:37]
	s_xor_b64 s[36:37], exec, s[44:45]
	s_cbranch_execz .LBB0_295
	v_add_u32_e32 v5, s32, v163
	v_add_u32_e32 v4, v5, v115
	v_add_u32_e32 v185, v5, v127
	v_add_u32_e32 v187, v5, v128
	v_add_u32_e32 v0, v5, v129
	ds_read_b128 v[8:11], v4
	ds_read_b128 v[12:15], v4 offset:4096
	ds_read_b128 v[96:99], v185
	ds_read_b128 v[188:191], v185 offset:4096
	ds_read_b128 v[192:195], v187
	ds_read_b128 v[196:199], v187 offset:4096
	ds_read_b128 v[226:229], v0
	ds_read_b128 v[230:233], v0 offset:4096
	s_waitcnt lgkmcnt(7)
	v_mfma_f32_32x32x16_f16 v[48:63], v[8:11], v[88:91], 0
	s_waitcnt lgkmcnt(6)
	v_mfma_f32_32x32x16_f16 v[64:79], v[12:15], v[88:91], 0
	s_waitcnt lgkmcnt(5)
	v_mfma_f32_32x32x16_f16 v[48:63], v[96:99], v[80:83], v[48:63]
	s_waitcnt lgkmcnt(4)
	v_mfma_f32_32x32x16_f16 v[64:79], v[188:191], v[80:83], v[64:79]
	s_waitcnt lgkmcnt(3)
	v_mfma_f32_32x32x16_f16 v[48:63], v[192:195], v[84:87], v[48:63]
	s_waitcnt lgkmcnt(2)
	v_mfma_f32_32x32x16_f16 v[64:79], v[196:199], v[84:87], v[64:79]
	s_waitcnt lgkmcnt(1)
	v_mfma_f32_32x32x16_f16 v[48:63], v[226:229], v[92:95], v[48:63]
	s_waitcnt lgkmcnt(0)
	v_mfma_f32_32x32x16_f16 v[64:79], v[230:233], v[92:95], v[64:79]
	s_nop 11
	v_max3_f32 v0, v48, s55, v64
	v_max3_f32 v0, v0, v49, v65
	v_max3_f32 v0, v0, v50, v66
	v_max3_f32 v0, v0, v51, v67
	v_max3_f32 v0, v0, v52, v68
	v_max3_f32 v0, v0, v53, v69
	v_max3_f32 v0, v0, v54, v70
	v_max3_f32 v0, v0, v55, v71
	v_max3_f32 v0, v0, v56, v72
	v_max3_f32 v0, v0, v57, v73
	v_max3_f32 v0, v0, v58, v74
	v_max3_f32 v0, v0, v59, v75
	v_max3_f32 v0, v0, v60, v76
	v_max3_f32 v0, v0, v61, v77
	v_max3_f32 v0, v0, v62, v78
	v_max3_f32 v0, v0, v63, v79
	v_mov_b32_e32 v4, v0
	s_nop 1
	v_permlane32_swap_b32_e32 v0, v4
	v_max3_f32 v4, v186, v0, v4
	v_sub_f32_e32 v0, v186, v4
	v_exp_f32_e32 v0, v0
	s_nop 0
	v_cmp_neq_f32_e32 vcc, 1.0, v0
	s_cbranch_vccz .LBB0_294
	v_mul_f32_e32 v30, v0, v30
	v_mul_f32_e32 v31, v0, v31
	v_mul_f32_e32 v28, v0, v28
	v_mul_f32_e32 v29, v0, v29
	v_mul_f32_e32 v26, v0, v26
	v_mul_f32_e32 v27, v0, v27
	v_mul_f32_e32 v24, v0, v24
	v_mul_f32_e32 v25, v0, v25
	v_mul_f32_e32 v22, v0, v22
	v_mul_f32_e32 v23, v0, v23
	v_mul_f32_e32 v20, v0, v20
	v_mul_f32_e32 v21, v0, v21
	v_mul_f32_e32 v18, v0, v18
	v_mul_f32_e32 v19, v0, v19
	v_mul_f32_e32 v16, v0, v16
	v_mul_f32_e32 v17, v0, v17
	v_mul_f32_e32 v46, v0, v46
	v_mul_f32_e32 v47, v0, v47
	v_mul_f32_e32 v44, v0, v44
	v_mul_f32_e32 v45, v0, v45
	v_mul_f32_e32 v42, v0, v42
	v_mul_f32_e32 v43, v0, v43
	v_mul_f32_e32 v40, v0, v40
	v_mul_f32_e32 v41, v0, v41
	v_mul_f32_e32 v38, v0, v38
	v_mul_f32_e32 v39, v0, v39
	v_mul_f32_e32 v36, v0, v36
	v_mul_f32_e32 v37, v0, v37
	v_mul_f32_e32 v34, v0, v34
	v_mul_f32_e32 v35, v0, v35
	v_mul_f32_e32 v32, v0, v32
	v_mul_f32_e32 v33, v0, v33
.LBB0_294:
	v_sub_f32_e32 v10, v65, v4
	v_exp_f32_e32 v15, v10
	v_sub_f32_e32 v10, v50, v4
	v_sub_f32_e32 v50, v71, v4
	v_sub_f32_e32 v6, v48, v4
	v_sub_f32_e32 v8, v64, v4
	v_sub_f32_e32 v48, v69, v4
	v_exp_f32_e32 v69, v50
	v_sub_f32_e32 v50, v56, v4
	v_exp_f32_e32 v6, v6
	v_exp_f32_e32 v14, v8
	v_sub_f32_e32 v9, v49, v4
	v_exp_f32_e32 v56, v50
	v_sub_f32_e32 v50, v72, v4
	v_exp_f32_e32 v9, v9
	v_sub_f32_e32 v11, v66, v4
	v_sub_f32_e32 v49, v70, v4
	v_exp_f32_e32 v70, v50
	v_sub_f32_e32 v50, v57, v4
	v_exp_f32_e32 v10, v10
	v_exp_f32_e32 v64, v11
	v_sub_f32_e32 v11, v51, v4
	v_sub_f32_e32 v12, v67, v4
	v_exp_f32_e32 v57, v50
	v_sub_f32_e32 v50, v73, v4
	v_exp_f32_e32 v11, v11
	v_exp_f32_e32 v65, v12
	v_sub_f32_e32 v12, v52, v4
	v_sub_f32_e32 v13, v68, v4
	v_exp_f32_e32 v71, v50
	v_sub_f32_e32 v50, v58, v4
	v_add_f32_e32 v7, 0, v6
	v_add_f32_e32 v8, 0, v14
	v_exp_f32_e32 v12, v12
	v_exp_f32_e32 v66, v13
	v_sub_f32_e32 v13, v53, v4
	v_exp_f32_e32 v58, v50
	v_sub_f32_e32 v50, v74, v4
	v_add_f32_e32 v7, v9, v7
	v_add_f32_e32 v8, v15, v8
	v_exp_f32_e32 v13, v13
	v_exp_f32_e32 v67, v48
	v_sub_f32_e32 v48, v54, v4
	v_exp_f32_e32 v72, v50
	v_sub_f32_e32 v50, v59, v4
	v_add_f32_e32 v7, v10, v7
	v_add_f32_e32 v8, v64, v8
	v_exp_f32_e32 v48, v48
	v_exp_f32_e32 v68, v49
	v_sub_f32_e32 v49, v55, v4
	v_exp_f32_e32 v73, v50
	v_sub_f32_e32 v50, v75, v4
	v_add_f32_e32 v7, v11, v7
	v_add_f32_e32 v8, v65, v8
	v_exp_f32_e32 v49, v49
	v_exp_f32_e32 v74, v50
	v_sub_f32_e32 v50, v60, v4
	v_add_f32_e32 v7, v12, v7
	v_add_f32_e32 v8, v66, v8
	v_exp_f32_e32 v60, v50
	v_sub_f32_e32 v50, v76, v4
	v_add_f32_e32 v7, v13, v7
	v_add_f32_e32 v8, v67, v8
	v_exp_f32_e32 v75, v50
	v_sub_f32_e32 v50, v61, v4
	v_add_f32_e32 v7, v48, v7
	v_add_f32_e32 v8, v68, v8
	v_exp_f32_e32 v61, v50
	v_sub_f32_e32 v50, v77, v4
	v_add_f32_e32 v7, v49, v7
	v_add_f32_e32 v8, v69, v8
	v_exp_f32_e32 v76, v50
	v_sub_f32_e32 v50, v62, v4
	v_add_f32_e32 v7, v56, v7
	v_add_f32_e32 v8, v70, v8
	v_exp_f32_e32 v62, v50
	v_sub_f32_e32 v50, v78, v4
	v_add_f32_e32 v7, v57, v7
	v_add_f32_e32 v8, v71, v8
	v_exp_f32_e32 v77, v50
	v_sub_f32_e32 v50, v63, v4
	v_add_f32_e32 v7, v58, v7
	v_add_f32_e32 v8, v72, v8
	v_exp_f32_e32 v63, v50
	v_sub_f32_e32 v50, v79, v4
	v_add_f32_e32 v7, v73, v7
	v_add_f32_e32 v8, v74, v8
	v_exp_f32_e32 v78, v50
	v_add_f32_e32 v7, v60, v7
	v_add_f32_e32 v8, v75, v8
	v_add_f32_e32 v7, v61, v7
	v_add_f32_e32 v8, v76, v8
	v_add_f32_e32 v7, v62, v7
	v_add_f32_e32 v8, v77, v8
	v_add_f32_e32 v7, v63, v7
	v_add_f32_e32 v8, v78, v8
	v_add_f32_e32 v59, v8, v7
	v_fmac_f32_e32 v59, v177, v0
	v_cvt_pkrtz_f16_f32 v7, v10, v11
	v_cvt_pkrtz_f16_f32 v8, v12, v13
	v_cvt_pkrtz_f16_f32 v6, v6, v9
	v_cvt_pkrtz_f16_f32 v9, v48, v49
	v_add_u32_e32 v0, v5, v172
	v_add_u32_e32 v196, v5, v170
	ds_read_b64 v[52:53], v0
	ds_read_b64 v[48:49], v0 offset:4096
	ds_read_b64 v[54:55], v196
	ds_read_b64 v[50:51], v196 offset:4096
	v_add_u32_e32 v0, v5, v169
	v_add_u32_e32 v196, v5, v168
	ds_read_b64 v[192:193], v0
	ds_read_b64 v[188:189], v0 offset:4096
	ds_read_b64 v[194:195], v196
	ds_read_b64 v[190:191], v196 offset:4096
	v_cvt_pkrtz_f16_f32 v10, v56, v57
	v_cvt_pkrtz_f16_f32 v11, v58, v73
	v_cvt_pkrtz_f16_f32 v12, v60, v61
	v_cvt_pkrtz_f16_f32 v13, v62, v63
	s_waitcnt lgkmcnt(4)
	v_mfma_f32_32x32x16_f16 v[32:47], v[48:51], v[6:9], v[32:47]
	v_mfma_f32_32x32x16_f16 v[16:31], v[52:55], v[6:9], v[16:31]
	v_add_u32_e32 v0, v5, v166
	v_add_u32_e32 v196, v5, v164
	ds_read_b64 v[52:53], v0
	ds_read_b64 v[48:49], v0 offset:4096
	ds_read_b64 v[54:55], v196 offset:8192
	ds_read_b64 v[50:51], v196 offset:12288
	v_cvt_pkrtz_f16_f32 v6, v14, v15
	v_cvt_pkrtz_f16_f32 v7, v64, v65
	v_cvt_pkrtz_f16_f32 v8, v66, v67
	v_cvt_pkrtz_f16_f32 v9, v68, v69
	s_waitcnt lgkmcnt(4)
	v_mfma_f32_32x32x16_f16 v[32:47], v[188:191], v[10:13], v[32:47]
	v_mfma_f32_32x32x16_f16 v[16:31], v[192:195], v[10:13], v[16:31]
	v_add_u32_e32 v0, v5, v175
	v_add_u32_e32 v196, v5, v173
	ds_read_b64 v[192:193], v0
	ds_read_b64 v[188:189], v0 offset:4096
	ds_read_b64 v[194:195], v196
	ds_read_b64 v[190:191], v196 offset:4096
	v_cvt_pkrtz_f16_f32 v13, v77, v78
	v_cvt_pkrtz_f16_f32 v10, v70, v71
	v_cvt_pkrtz_f16_f32 v11, v72, v74
	v_cvt_pkrtz_f16_f32 v12, v75, v76
	s_waitcnt lgkmcnt(4)
	v_mfma_f32_32x32x16_f16 v[32:47], v[48:51], v[6:9], v[32:47]
	v_mfma_f32_32x32x16_f16 v[16:31], v[52:55], v[6:9], v[16:31]
	s_waitcnt lgkmcnt(0)
	v_mfma_f32_32x32x16_f16 v[32:47], v[188:191], v[10:13], v[32:47]
	v_mfma_f32_32x32x16_f16 v[16:31], v[192:195], v[10:13], v[16:31]
.LBB0_295:
	s_andn2_saveexec_b64 s[36:37], s[36:37]
	s_cbranch_execz .LBB0_263
	v_add_u32_e32 v4, s54, v120
	v_cmp_ge_u32_e32 vcc, v4, v122
	v_cmp_le_u32_e64 s[44:45], v4, v130
	s_and_b64 s[50:51], vcc, s[44:45]
	s_and_saveexec_b64 s[44:45], s[50:51]
	s_cbranch_execz .LBB0_262
	v_add_u32_e32 v185, s32, v163
	v_add_u32_e32 v4, v185, v115
	ds_read_b128 v[64:67], v4
	ds_read_b128 v[68:71], v4 offset:4096
	v_add_u32_e32 v4, v185, v127
	ds_read_b128 v[96:99], v4
	ds_read_b128 v[104:107], v4 offset:4096
	v_add_u32_e32 v4, v185, v128
	v_add_u32_e32 v0, v185, v129
	ds_read_b128 v[12:15], v4
	ds_read_b128 v[100:103], v4 offset:4096
	ds_read_b128 v[4:7], v0
	ds_read_b128 v[8:11], v0 offset:4096
	s_and_saveexec_b64 s[50:51], s[42:43]
	s_xor_b64 s[50:51], exec, s[50:51]
	s_cbranch_execz .LBB0_301
	s_waitcnt lgkmcnt(0)
	v_mfma_f32_32x32x16_f16 v[48:63], v[68:71], v[88:91], 0
	v_mfma_f32_32x32x16_f16 v[48:63], v[104:107], v[80:83], v[48:63]
	v_mfma_f32_32x32x16_f16 v[48:63], v[100:103], v[84:87], v[48:63]
	v_mfma_f32_32x32x16_f16 v[48:63], v[8:11], v[92:95], v[48:63]
	ds_read_b32 v8, v149 offset:16
	ds_read_b32 v9, v147 offset:16
	ds_read_b32 v11, v145 offset:16
	ds_read_b32 v72, v143 offset:16
	ds_read_b32 v102, v154 offset:16
	ds_read_b32 v103, v153 offset:16
	ds_read_b32 v104, v152 offset:16
	ds_read_b32 v105, v151 offset:16
	s_waitcnt lgkmcnt(0)
	s_nop 2
	v_add_f32_e32 v100, v48, v8
	v_add_f32_e32 v8, v51, v72
	v_mfma_f32_32x32x16_f16 v[64:79], v[64:67], v[88:91], 0
	v_add_f32_e32 v10, v49, v9
	v_add_f32_e32 v9, v50, v11
	v_mfma_f32_32x32x16_f16 v[64:79], v[96:99], v[80:83], v[64:79]
	ds_read_b32 v96, v162 offset:16
	ds_read_b32 v11, v161 offset:16
	ds_read_b32 v48, v160 offset:16
	ds_read_b32 v49, v159 offset:16
	ds_read_b32 v50, v158 offset:16
	ds_read_b32 v98, v157 offset:16
	ds_read_b32 v99, v156 offset:16
	ds_read_b32 v101, v155 offset:16
	s_waitcnt lgkmcnt(0)
	v_add_f32_e32 v97, v52, v96
	v_add_f32_e32 v96, v53, v11
	v_add_f32_e32 v53, v54, v48
	v_add_f32_e32 v52, v55, v49
	v_add_f32_e32 v51, v56, v50
	v_add_f32_e32 v50, v57, v98
	v_mfma_f32_32x32x16_f16 v[64:79], v[12:15], v[84:87], v[64:79]
	ds_read_b32 v11, v134 offset:16
	ds_read_b32 v12, v133 offset:16
	ds_read_b32 v48, v132 offset:16
	ds_read_b32 v0, v131 offset:16
	v_add_f32_e32 v15, v58, v99
	v_add_f32_e32 v14, v59, v101
	v_add_f32_e32 v13, v60, v102
	v_mfma_f32_32x32x16_f16 v[64:79], v[4:7], v[92:95], v[64:79]
	v_add_f32_e32 v6, v62, v104
	v_add_f32_e32 v4, v63, v105
	s_waitcnt lgkmcnt(0)
	s_nop 8
	v_add_f32_e32 v5, v79, v0
	v_max3_f32 v0, v100, s55, v10
	v_max3_f32 v0, v0, v9, v8
	v_max3_f32 v0, v0, v97, v96
	v_max3_f32 v0, v0, v53, v52
	v_max3_f32 v0, v0, v51, v50
	v_add_f32_e32 v49, v76, v11
	v_max3_f32 v0, v0, v15, v14
	v_add_f32_e32 v12, v77, v12
	v_add_f32_e32 v11, v61, v103
	v_max3_f32 v0, v0, v49, v13
	v_add_f32_e32 v7, v78, v48
	v_max3_f32 v0, v0, v12, v11
	v_max3_f32 v0, v0, v7, v6
	v_max3_f32 v0, v0, v5, v4
	v_mov_b32_e32 v48, v0
	s_nop 1
	v_permlane32_swap_b32_e32 v0, v48
	v_max3_f32 v48, v186, v0, v48
	v_sub_f32_e32 v0, v186, v48
	v_exp_f32_e32 v0, v0
	s_nop 0
	v_cmp_neq_f32_e32 vcc, 1.0, v0
	s_cbranch_vccz .LBB0_300
	v_mul_f32_e32 v30, v0, v30
	v_mul_f32_e32 v31, v0, v31
	v_mul_f32_e32 v28, v0, v28
	v_mul_f32_e32 v29, v0, v29
	v_mul_f32_e32 v26, v0, v26
	v_mul_f32_e32 v27, v0, v27
	v_mul_f32_e32 v24, v0, v24
	v_mul_f32_e32 v25, v0, v25
	v_mul_f32_e32 v22, v0, v22
	v_mul_f32_e32 v23, v0, v23
	v_mul_f32_e32 v20, v0, v20
	v_mul_f32_e32 v21, v0, v21
	v_mul_f32_e32 v18, v0, v18
	v_mul_f32_e32 v19, v0, v19
	v_mul_f32_e32 v16, v0, v16
	v_mul_f32_e32 v17, v0, v17
	v_mul_f32_e32 v46, v0, v46
	v_mul_f32_e32 v47, v0, v47
	v_mul_f32_e32 v44, v0, v44
	v_mul_f32_e32 v45, v0, v45
	v_mul_f32_e32 v42, v0, v42
	v_mul_f32_e32 v43, v0, v43
	v_mul_f32_e32 v40, v0, v40
	v_mul_f32_e32 v41, v0, v41
	v_mul_f32_e32 v38, v0, v38
	v_mul_f32_e32 v39, v0, v39
	v_mul_f32_e32 v36, v0, v36
	v_mul_f32_e32 v37, v0, v37
	v_mul_f32_e32 v34, v0, v34
	v_mul_f32_e32 v35, v0, v35
	v_mul_f32_e32 v32, v0, v32
	v_mul_f32_e32 v33, v0, v33
.LBB0_300:
	v_sub_f32_e32 v54, v100, v48
	v_exp_f32_e32 v58, v54
	v_sub_f32_e32 v10, v10, v48
	v_sub_f32_e32 v9, v9, v48
	v_exp_f32_e32 v59, v10
	v_exp_f32_e32 v60, v9
	v_sub_f32_e32 v8, v8, v48
	v_exp_f32_e32 v61, v8
	v_sub_f32_e32 v8, v97, v48
	v_sub_f32_e32 v9, v96, v48
	v_add_f32_e32 v10, 0, v58
	v_exp_f32_e32 v62, v8
	v_exp_f32_e32 v63, v9
	v_sub_f32_e32 v9, v53, v48
	v_add_f32_e32 v8, v59, v10
	v_exp_f32_e32 v64, v9
	v_sub_f32_e32 v9, v52, v48
	v_add_f32_e32 v8, v60, v8
	v_exp_f32_e32 v65, v9
	v_sub_f32_e32 v9, v51, v48
	v_add_f32_e32 v8, v61, v8
	v_exp_f32_e32 v66, v9
	v_sub_f32_e32 v9, v50, v48
	v_add_f32_e32 v8, v62, v8
	v_exp_f32_e32 v67, v9
	v_sub_f32_e32 v9, v15, v48
	v_add_f32_e32 v8, v63, v8
	v_exp_f32_e32 v15, v9
	v_sub_f32_e32 v9, v14, v48
	v_add_f32_e32 v8, v64, v8
	v_exp_f32_e32 v14, v9
	v_sub_f32_e32 v9, v49, v48
	v_sub_f32_e32 v10, v13, v48
	v_add_f32_e32 v8, v65, v8
	v_exp_f32_e32 v49, v9
	v_exp_f32_e32 v68, v10
	v_sub_f32_e32 v10, v12, v48
	v_add_f32_e32 v8, v66, v8
	v_exp_f32_e32 v54, v10
	v_sub_f32_e32 v10, v11, v48
	v_sub_f32_e32 v7, v7, v48
	v_add_f32_e32 v8, v67, v8
	v_exp_f32_e32 v69, v10
	v_exp_f32_e32 v55, v7
	v_add_f32_e32 v8, v15, v8
	v_add_f32_e32 v8, v14, v8
	v_add_f32_e32 v9, 0, v49
	v_add_f32_e32 v7, v68, v8
	v_add_f32_e32 v8, v54, v9
	v_sub_f32_e32 v6, v6, v48
	v_add_u32_e32 v2, v185, v169
	v_add_u32_e32 v1, v185, v168
	v_add_f32_e32 v70, v69, v7
	v_add_f32_e32 v71, v55, v8
	v_exp_f32_e32 v72, v6
	ds_read2st64_b64 v[6:9], v2 offset1:8
	ds_read2st64_b64 v[10:13], v1 offset1:8
	v_sub_f32_e32 v1, v5, v48
	v_exp_f32_e32 v1, v1
	v_add_u32_e32 v2, v185, v166
	s_waitcnt lgkmcnt(0)
	v_mov_b32_e32 v50, v6
	v_mov_b32_e32 v51, v7
	v_mov_b32_e32 v52, v10
	v_mov_b32_e32 v53, v11
	v_cvt_pkrtz_f16_f32 v56, v49, v54
	v_cvt_pkrtz_f16_f32 v57, v55, v1
	v_mov_b32_e32 v54, v3
	v_mov_b32_e32 v55, v3
	v_mov_b32_e32 v10, v8
	v_mov_b32_e32 v11, v9
	ds_read2st64_b64 v[6:9], v2 offset1:8
	v_add_u32_e32 v2, v185, v164
	v_mfma_f32_32x32x16_f16 v[16:31], v[50:53], v[54:57], v[16:31]
	ds_read2st64_b64 v[50:53], v2 offset0:16 offset1:24
	v_sub_f32_e32 v2, v4, v48
	s_waitcnt lgkmcnt(0)
	v_mov_b32_e32 v4, v6
	v_mov_b32_e32 v5, v7
	v_exp_f32_e32 v2, v2
	v_mov_b32_e32 v6, v50
	v_mov_b32_e32 v7, v51
	v_mfma_f32_32x32x16_f16 v[32:47], v[10:13], v[54:57], v[32:47]
	v_mov_b32_e32 v50, v8
	v_mov_b32_e32 v51, v9
	v_cvt_pkrtz_f16_f32 v10, v58, v59
	v_cvt_pkrtz_f16_f32 v11, v60, v61
	v_cvt_pkrtz_f16_f32 v12, v62, v63
	v_cvt_pkrtz_f16_f32 v13, v64, v65
	v_add_u32_e32 v8, v185, v173
	ds_read2st64_b64 v[54:57], v8 offset1:8
	v_mfma_f32_32x32x16_f16 v[16:31], v[4:7], v[10:13], v[16:31]
	v_add_u32_e32 v4, v185, v175
	ds_read2st64_b64 v[4:7], v4 offset1:8
	v_add_f32_e32 v1, v1, v71
	s_waitcnt lgkmcnt(0)
	v_mov_b32_e32 v8, v4
	v_mfma_f32_32x32x16_f16 v[32:47], v[50:53], v[10:13], v[32:47]
	v_mov_b32_e32 v9, v5
	v_mov_b32_e32 v10, v54
	v_mov_b32_e32 v11, v55
	v_mov_b32_e32 v54, v6
	v_mov_b32_e32 v55, v7
	v_cvt_pkrtz_f16_f32 v12, v66, v67
	v_cvt_pkrtz_f16_f32 v13, v15, v14
	v_cvt_pkrtz_f16_f32 v14, v68, v69
	v_cvt_pkrtz_f16_f32 v15, v72, v2
	v_add_f32_e32 v4, v72, v70
	v_add_f32_e32 v2, v2, v4
	v_mfma_f32_32x32x16_f16 v[16:31], v[8:11], v[12:15], v[16:31]
	v_add_f32_e32 v1, v1, v2
	v_fmac_f32_e32 v1, v177, v0
	v_mov_b32_e32 v177, v1
	v_mfma_f32_32x32x16_f16 v[32:47], v[54:57], v[12:15], v[32:47]
